# v31 + S5 pass A: MFMA<->VALU interleave - the in-projection MFMAs of step t+1 are issued inside step t's fmac stream into a second accumulator set (two steps per iteration)
# speedup vs baseline: 1.0001x; 1.0001x over previous
; #define LAS __attribute__((address_space(3)))
; __device__ __forceinline__ unsigned cvtpk_s(float lo, float hi) { f32x2_t v = {lo, hi}; bf16x2_t b = __builtin_convertvector(v, bf16x2_t); return __builtin_bit_cast(unsigned, b); }
; template <bool FULL>
; __device__ __forceinline__ void s5_pass(const Params& P, LAS unsigned char* lds, int bx, int tid_in) {
;     ...
;         bf16x8 ua = *(const bf16x8*)u32p, ub0, ub1;
;         if (FULL) { ub0 = *(const bf16x8*)u16p; ub1 = *(const bf16x8*)(u16p + (size_t)4 * SEQ * BR); }
;         for (int t0 = 0; t0 < S5_SEGLEN; t0 += 16) {
;             const bf16x8 ca = ua; bf16x8 cb0, cb1; if (FULL) { cb0 = ub0; cb1 = ub1; }
;             if (t0 + 16 < S5_SEGLEN) { const size_t o = (size_t)(t0 + 16) * BR; ua = *(const bf16x8*)(u32p + o); if (FULL) { ub0 = *(const bf16x8*)(u16p + o); ub1 = *(const bf16x8*)(u16p + o + (size_t)4 * SEQ * BR); } }
;             if (FULL && kg >= 2) { cb0 = (bf16x8){0, 0, 0, 0, 0, 0, 0, 0}; cb1 = cb0; }
;             f32x16 acc[4];
; #pragma unroll
;             for (int j = 0; j < 4; ++j) {
; #pragma unroll
;                 for (int r = 0; r < 16; ++r) acc[j][r] = 0.f;
;                 acc[j] = __builtin_amdgcn_mfma_f32_32x32x16_bf16(ca, bfr[j], acc[j], 0, 0, 0); }
; #pragma unroll
;             for (int r = 0; r < 16; ++r) {
;                 const float n0r = ar0 * h0r - ai0 * h0i + acc[0][r], n0i = ar0 * h0i + ai0 * h0r + acc[2][r];
;                 const float n1r = ar1 * h1r - ai1 * h1i + acc[1][r], n1i = ar1 * h1i + ai1 * h1r + acc[3][r];
;                 h0r = n0r; h0i = n0i; h1r = n1r; h1i = n1i;
;                 if (FULL) { *(LAS unsigned*)(hl + (16 * hi + r) * HROW + r32 * 4) = cvtpk_s(n0r, n0i);
;                     *(LAS unsigned*)(hl + (16 * hi + r) * HROW + (32 + r32) * 4) = cvtpk_s(n1r, n1i); }
;             }
.LBB0_403:
	s_and_b32 s12, s4, 0xfffffe00
	s_cmpk_eq_i32 s12, 0xe00
	s_cbranch_scc1 .LBB0_402
	s_ashr_i32 s13, s12, 31
	s_bfe_u32 s5, s4, 0x20007
	v_mov_b32_e32 v1, s13
	v_or_b32_e32 v0, s12, v88
	v_lshl_add_u32 v84, s5, 12, v106
	s_and_b32 s8, s4, 0x7f
	v_lshl_add_u64 v[0:1], v[0:1], 0, v[84:85]
	v_lshl_or_b32 v2, s8, 9, v107
	v_lshl_or_b32 v84, s8, 12, v108
	v_or_b32_e32 v4, s5, v89
	global_load_dwordx2 v[96:97], v2, s[46:47]
	global_load_dwordx2 v[98:99], v2, s[46:47] offset:256
	v_lshl_add_u64 v[2:3], v[86:87], 0, v[84:85]
	v_lshlrev_b32_e32 v84, 12, v4
	v_lshl_add_u64 v[4:5], v[84:85], 0, s[12:13]
	v_or_b32_e32 v4, v4, v88
	v_lshlrev_b64 v[4:5], 12, v[4:5]
	v_lshl_add_u64 v[4:5], s[34:35], 0, v[4:5]
	s_lshl_b32 s8, s8, 5
	v_lshl_add_u64 v[4:5], v[4:5], 0, s[8:9]
	v_mov_b32_e32 v95, v85
	v_lshl_add_u64 v[4:5], v[4:5], 0, v[94:95]
	v_lshlrev_b64 v[0:1], 12, v[0:1]
	s_and_b32 s5, s18, 0x7f
	v_lshl_or_b32 v0, s5, 5, v0
	v_mov_b32_e32 v34, 0
	v_lshl_add_u64 v[100:101], v[92:93], 0, v[0:1]
	global_load_dwordx4 v[64:67], v[2:3], off
	global_load_dwordx4 v[68:71], v[2:3], off offset:1024
	global_load_dwordx4 v[72:75], v[2:3], off offset:2048
	global_load_dwordx4 v[76:79], v[2:3], off offset:3072
	v_mov_b32_e32 v116, v4
	v_mov_b32_e32 v117, v5
	s_add_i32 m0, s50, 0
	s_nop 0
	global_load_lds_dwordx4 v[116:117], off
	v_lshl_add_u64 v[116:117], v[116:117], 0, s[10:11]
	s_add_i32 m0, s50, 1024
	s_nop 0
	global_load_lds_dwordx4 v[116:117], off
	v_lshl_add_u64 v[116:117], v[116:117], 0, s[10:11]
	s_add_i32 m0, s50, 2048
	s_nop 0
	global_load_lds_dwordx4 v[116:117], off
	v_lshl_add_u64 v[116:117], v[116:117], 0, s[10:11]
	s_add_i32 m0, s50, 3072
	s_nop 0
	global_load_lds_dwordx4 v[116:117], off
	v_lshl_add_u64 v[116:117], v[116:117], 0, s[10:11]
	s_add_i32 m0, s50, 4096
	s_nop 0
	global_load_lds_dwordx4 v[116:117], off
	v_lshl_add_u64 v[116:117], v[116:117], 0, s[10:11]
	s_add_i32 m0, s50, 5120
	s_nop 0
	global_load_lds_dwordx4 v[116:117], off
	v_lshl_add_u64 v[116:117], v[116:117], 0, s[10:11]
	s_add_i32 m0, s50, 6144
	s_nop 0
	global_load_lds_dwordx4 v[116:117], off
	v_lshl_add_u64 v[116:117], v[116:117], 0, s[10:11]
	s_add_i32 m0, s50, 7168
	s_nop 0
	global_load_lds_dwordx4 v[116:117], off
	v_lshl_add_u64 v[116:117], v[116:117], 0, s[10:11]
	s_add_i32 s51, s50, 1024
	v_add_u32_e32 v115, s50, v114
	v_mov_b32_e32 v130, 0
	v_mov_b32_e32 v131, 0
	v_mov_b32_e32 v132, 0
	v_mov_b32_e32 v133, 0
	s_movk_i32 s56, 16
	s_waitcnt vmcnt(0)
	ds_read_b128 v[120:123], v115
	v_xor_b32_e32 v126, 0x80000000, v97
	v_xor_b32_e32 v129, 0x80000000, v99
	s_mov_b32 m0, s50
	s_waitcnt lgkmcnt(0)
	global_load_lds_dwordx4 v[116:117], off
	v_lshl_add_u64 v[116:117], v[116:117], 0, s[10:11]
	s_mov_b32 s53, 9
	v_mfma_f32_32x32x16_bf16 v[0:15], v[120:123], v[64:67], 0
	v_mfma_f32_32x32x16_bf16 v[16:31], v[120:123], v[72:75], 0
	v_mfma_f32_32x32x16_bf16 v[32:47], v[120:123], v[68:71], 0
	v_mfma_f32_32x32x16_bf16 v[48:63], v[120:123], v[76:79], 0
	.p2align 6
.Ls5a_step:
	s_cmp_lt_u32 s53, 31
	s_cselect_b32 s54, 0x10000, 0
	s_cmp_lt_u32 s53, 32
	s_cselect_b32 m0, s51, s52
	s_add_i32 s53, s53, 1
	v_add_u32_e32 v115, s51, v114
	s_add_i32 s51, s51, 1024
	s_cmp_eq_u32 s51, s52
	s_cselect_b32 s51, s50, s51
	s_nop 1
	v_fmac_f32_e32 v0, v96, v130
	v_fmac_f32_e32 v16, v96, v131
	v_fmac_f32_e32 v32, v98, v132
	v_fmac_f32_e32 v48, v98, v133
	v_fmac_f32_e32 v0, v126, v131
	v_fmac_f32_e32 v16, v97, v130
	v_fmac_f32_e32 v32, v129, v133
	v_fmac_f32_e32 v48, v99, v132
	v_fmac_f32_e32 v1, v96, v0
	v_fmac_f32_e32 v17, v96, v16
	v_fmac_f32_e32 v33, v98, v32
	v_fmac_f32_e32 v49, v98, v48
	v_fmac_f32_e32 v1, v126, v16
	v_fmac_f32_e32 v17, v97, v0
	v_fmac_f32_e32 v33, v129, v48
	v_fmac_f32_e32 v49, v99, v32
	s_waitcnt vmcnt(7)
	ds_read_b128 v[120:123], v115
	v_fmac_f32_e32 v2, v96, v1
	v_fmac_f32_e32 v18, v96, v17
	v_fmac_f32_e32 v34, v98, v33
	v_fmac_f32_e32 v50, v98, v49
	v_fmac_f32_e32 v2, v126, v17
	v_fmac_f32_e32 v18, v97, v1
	v_fmac_f32_e32 v34, v129, v49
	v_fmac_f32_e32 v50, v99, v33
	v_fmac_f32_e32 v3, v96, v2
	v_fmac_f32_e32 v19, v96, v18
	v_fmac_f32_e32 v35, v98, v34
	v_fmac_f32_e32 v51, v98, v50
	v_fmac_f32_e32 v3, v126, v18
	v_fmac_f32_e32 v19, v97, v2
	v_fmac_f32_e32 v35, v129, v50
	v_fmac_f32_e32 v51, v99, v34
	s_waitcnt lgkmcnt(0)
; #define LAS __attribute__((address_space(3)))
; __device__ __forceinline__ unsigned cvtpk_s(float lo, float hi) { f32x2_t v = {lo, hi}; bf16x2_t b = __builtin_convertvector(v, bf16x2_t); return __builtin_bit_cast(unsigned, b); }
; template <bool FULL>
; __device__ __forceinline__ void s5_pass(const Params& P, LAS unsigned char* lds, int bx, int tid_in) {
;     ...
;         for (int t0 = 0; t0 < S5_SEGLEN; t0 += 16) {
;             const bf16x8 ca = ua; bf16x8 cb0, cb1; if (FULL) { cb0 = ub0; cb1 = ub1; }
;             if (t0 + 16 < S5_SEGLEN) { const size_t o = (size_t)(t0 + 16) * BR; ua = *(const bf16x8*)(u32p + o); if (FULL) { ub0 = *(const bf16x8*)(u16p + o); ub1 = *(const bf16x8*)(u16p + o + (size_t)4 * SEQ * BR); } }
;             if (FULL && kg >= 2) { cb0 = (bf16x8){0, 0, 0, 0, 0, 0, 0, 0}; cb1 = cb0; }
;             f32x16 acc[4];
; #pragma unroll
;             for (int j = 0; j < 4; ++j) {
; #pragma unroll
;                 for (int r = 0; r < 16; ++r) acc[j][r] = 0.f;
;                 acc[j] = __builtin_amdgcn_mfma_f32_32x32x16_bf16(ca, bfr[j], acc[j], 0, 0, 0); }
; #pragma unroll
;             for (int r = 0; r < 16; ++r) {
;                 const float n0r = ar0 * h0r - ai0 * h0i + acc[0][r], n0i = ar0 * h0i + ai0 * h0r + acc[2][r];
;                 const float n1r = ar1 * h1r - ai1 * h1i + acc[1][r], n1i = ar1 * h1i + ai1 * h1r + acc[3][r];
;                 h0r = n0r; h0i = n0i; h1r = n1r; h1i = n1i;
;                 if (FULL) { *(LAS unsigned*)(hl + (16 * hi + r) * HROW + r32 * 4) = cvtpk_s(n0r, n0i);
;                     *(LAS unsigned*)(hl + (16 * hi + r) * HROW + (32 + r32) * 4) = cvtpk_s(n1r, n1i); }
;             }
	v_mfma_f32_32x32x16_bf16 v[140:155], v[120:123], v[64:67], 0
	v_fmac_f32_e32 v4, v96, v3
	v_fmac_f32_e32 v20, v96, v19
	v_fmac_f32_e32 v36, v98, v35
	v_fmac_f32_e32 v52, v98, v51
	v_fmac_f32_e32 v4, v126, v19
	v_fmac_f32_e32 v20, v97, v3
	v_fmac_f32_e32 v36, v129, v51
	v_fmac_f32_e32 v52, v99, v35
	v_fmac_f32_e32 v5, v96, v4
	v_fmac_f32_e32 v21, v96, v20
	v_fmac_f32_e32 v37, v98, v36
	v_fmac_f32_e32 v53, v98, v52
	v_fmac_f32_e32 v5, v126, v20
	v_fmac_f32_e32 v21, v97, v4
	v_fmac_f32_e32 v37, v129, v52
	v_fmac_f32_e32 v53, v99, v36
	v_fmac_f32_e32 v6, v96, v5
	v_fmac_f32_e32 v22, v96, v21
	v_fmac_f32_e32 v38, v98, v37
	v_fmac_f32_e32 v54, v98, v53
	v_fmac_f32_e32 v6, v126, v21
	v_fmac_f32_e32 v22, v97, v5
	v_fmac_f32_e32 v38, v129, v53
	v_fmac_f32_e32 v54, v99, v37
	v_mfma_f32_32x32x16_bf16 v[156:171], v[120:123], v[72:75], 0
	v_fmac_f32_e32 v7, v96, v6
	v_fmac_f32_e32 v23, v96, v22
	v_fmac_f32_e32 v39, v98, v38
	v_fmac_f32_e32 v55, v98, v54
	v_fmac_f32_e32 v7, v126, v22
	v_fmac_f32_e32 v23, v97, v6
	v_fmac_f32_e32 v39, v129, v54
	v_fmac_f32_e32 v55, v99, v38
	v_fmac_f32_e32 v8, v96, v7
	v_fmac_f32_e32 v24, v96, v23
	v_fmac_f32_e32 v40, v98, v39
	v_fmac_f32_e32 v56, v98, v55
	v_fmac_f32_e32 v8, v126, v23
	v_fmac_f32_e32 v24, v97, v7
	v_fmac_f32_e32 v40, v129, v55
	v_fmac_f32_e32 v56, v99, v39
	v_fmac_f32_e32 v9, v96, v8
	v_fmac_f32_e32 v25, v96, v24
	v_fmac_f32_e32 v41, v98, v40
	v_fmac_f32_e32 v57, v98, v56
	v_fmac_f32_e32 v9, v126, v24
	v_fmac_f32_e32 v25, v97, v8
	v_fmac_f32_e32 v41, v129, v56
	v_fmac_f32_e32 v57, v99, v40
	v_mfma_f32_32x32x16_bf16 v[172:187], v[120:123], v[68:71], 0
	v_fmac_f32_e32 v10, v96, v9
	v_fmac_f32_e32 v26, v96, v25
	v_fmac_f32_e32 v42, v98, v41
	v_fmac_f32_e32 v58, v98, v57
	v_fmac_f32_e32 v10, v126, v25
	v_fmac_f32_e32 v26, v97, v9
	v_fmac_f32_e32 v42, v129, v57
	v_fmac_f32_e32 v58, v99, v41
	v_fmac_f32_e32 v11, v96, v10
	v_fmac_f32_e32 v27, v96, v26
	v_fmac_f32_e32 v43, v98, v42
	v_fmac_f32_e32 v59, v98, v58
	v_fmac_f32_e32 v11, v126, v26
	v_fmac_f32_e32 v27, v97, v10
	v_fmac_f32_e32 v43, v129, v58
	v_fmac_f32_e32 v59, v99, v42
	v_fmac_f32_e32 v12, v96, v11
	v_fmac_f32_e32 v28, v96, v27
	v_fmac_f32_e32 v44, v98, v43
	v_fmac_f32_e32 v60, v98, v59
	v_fmac_f32_e32 v12, v126, v27
	v_fmac_f32_e32 v28, v97, v11
	v_fmac_f32_e32 v44, v129, v59
	v_fmac_f32_e32 v60, v99, v43
	v_mfma_f32_32x32x16_bf16 v[188:203], v[120:123], v[76:79], 0
	v_fmac_f32_e32 v13, v96, v12
	v_fmac_f32_e32 v29, v96, v28
	v_fmac_f32_e32 v45, v98, v44
	v_fmac_f32_e32 v61, v98, v60
	v_fmac_f32_e32 v13, v126, v28
	v_fmac_f32_e32 v29, v97, v12
	v_fmac_f32_e32 v45, v129, v60
	v_fmac_f32_e32 v61, v99, v44
	v_fmac_f32_e32 v14, v96, v13
	v_fmac_f32_e32 v30, v96, v29
	v_fmac_f32_e32 v46, v98, v45
	v_fmac_f32_e32 v62, v98, v61
	v_fmac_f32_e32 v14, v126, v29
	v_fmac_f32_e32 v30, v97, v13
	v_fmac_f32_e32 v46, v129, v61
	v_fmac_f32_e32 v62, v99, v45
	v_fmac_f32_e32 v15, v96, v14
	v_fmac_f32_e32 v31, v96, v30
	v_fmac_f32_e32 v47, v98, v46
	v_fmac_f32_e32 v63, v98, v62
	v_fmac_f32_e32 v15, v126, v30
	v_fmac_f32_e32 v31, v97, v14
	v_fmac_f32_e32 v47, v129, v62
	v_fmac_f32_e32 v63, v99, v46
	v_mov_b32_e32 v130, v15
	v_mov_b32_e32 v131, v31
	v_mov_b32_e32 v132, v47
	v_mov_b32_e32 v133, v63
	global_load_lds_dwordx4 v[116:117], off
	v_lshl_add_u64 v[116:117], v[116:117], 0, s[54:55]
	s_cmp_lt_u32 s53, 31
	s_cselect_b32 s54, 0x10000, 0
	s_cmp_lt_u32 s53, 32
	s_cselect_b32 m0, s51, s52
	s_add_i32 s53, s53, 1
	v_add_u32_e32 v115, s51, v114
	s_add_i32 s51, s51, 1024
	s_cmp_eq_u32 s51, s52
	s_cselect_b32 s51, s50, s51
	s_nop 1
	v_fmac_f32_e32 v140, v96, v130
	v_fmac_f32_e32 v156, v96, v131
	v_fmac_f32_e32 v172, v98, v132
	v_fmac_f32_e32 v188, v98, v133
	v_fmac_f32_e32 v140, v126, v131
	v_fmac_f32_e32 v156, v97, v130
	v_fmac_f32_e32 v172, v129, v133
	v_fmac_f32_e32 v188, v99, v132
	v_fmac_f32_e32 v141, v96, v140
	v_fmac_f32_e32 v157, v96, v156
	v_fmac_f32_e32 v173, v98, v172
	v_fmac_f32_e32 v189, v98, v188
	v_fmac_f32_e32 v141, v126, v156
	v_fmac_f32_e32 v157, v97, v140
	v_fmac_f32_e32 v173, v129, v188
	v_fmac_f32_e32 v189, v99, v172
	s_waitcnt vmcnt(7)
; #define LAS __attribute__((address_space(3)))
; __device__ __forceinline__ unsigned cvtpk_s(float lo, float hi) { f32x2_t v = {lo, hi}; bf16x2_t b = __builtin_convertvector(v, bf16x2_t); return __builtin_bit_cast(unsigned, b); }
; template <bool FULL>
; __device__ __forceinline__ void s5_pass(const Params& P, LAS unsigned char* lds, int bx, int tid_in) {
;     ...
;         for (int t0 = 0; t0 < S5_SEGLEN; t0 += 16) {
;             const bf16x8 ca = ua; bf16x8 cb0, cb1; if (FULL) { cb0 = ub0; cb1 = ub1; }
;             if (t0 + 16 < S5_SEGLEN) { const size_t o = (size_t)(t0 + 16) * BR; ua = *(const bf16x8*)(u32p + o); if (FULL) { ub0 = *(const bf16x8*)(u16p + o); ub1 = *(const bf16x8*)(u16p + o + (size_t)4 * SEQ * BR); } }
;             if (FULL && kg >= 2) { cb0 = (bf16x8){0, 0, 0, 0, 0, 0, 0, 0}; cb1 = cb0; }
;             f32x16 acc[4];
; #pragma unroll
;             for (int j = 0; j < 4; ++j) {
; #pragma unroll
;                 for (int r = 0; r < 16; ++r) acc[j][r] = 0.f;
;                 acc[j] = __builtin_amdgcn_mfma_f32_32x32x16_bf16(ca, bfr[j], acc[j], 0, 0, 0); }
; #pragma unroll
;             for (int r = 0; r < 16; ++r) {
;                 const float n0r = ar0 * h0r - ai0 * h0i + acc[0][r], n0i = ar0 * h0i + ai0 * h0r + acc[2][r];
;                 const float n1r = ar1 * h1r - ai1 * h1i + acc[1][r], n1i = ar1 * h1i + ai1 * h1r + acc[3][r];
;                 h0r = n0r; h0i = n0i; h1r = n1r; h1i = n1i;
;                 if (FULL) { *(LAS unsigned*)(hl + (16 * hi + r) * HROW + r32 * 4) = cvtpk_s(n0r, n0i);
;                     *(LAS unsigned*)(hl + (16 * hi + r) * HROW + (32 + r32) * 4) = cvtpk_s(n1r, n1i); }
;             }
;     ...
;         if (!FULL) SEG[(size_t)task * 64 + lane] = (f32x4){h0r, h0i, h1r, h1i};
	ds_read_b128 v[120:123], v115
	v_fmac_f32_e32 v142, v96, v141
	v_fmac_f32_e32 v158, v96, v157
	v_fmac_f32_e32 v174, v98, v173
	v_fmac_f32_e32 v190, v98, v189
	v_fmac_f32_e32 v142, v126, v157
	v_fmac_f32_e32 v158, v97, v141
	v_fmac_f32_e32 v174, v129, v189
	v_fmac_f32_e32 v190, v99, v173
	v_fmac_f32_e32 v143, v96, v142
	v_fmac_f32_e32 v159, v96, v158
	v_fmac_f32_e32 v175, v98, v174
	v_fmac_f32_e32 v191, v98, v190
	v_fmac_f32_e32 v143, v126, v158
	v_fmac_f32_e32 v159, v97, v142
	v_fmac_f32_e32 v175, v129, v190
	v_fmac_f32_e32 v191, v99, v174
	s_waitcnt lgkmcnt(0)
	v_mfma_f32_32x32x16_bf16 v[0:15], v[120:123], v[64:67], 0
	v_fmac_f32_e32 v144, v96, v143
	v_fmac_f32_e32 v160, v96, v159
	v_fmac_f32_e32 v176, v98, v175
	v_fmac_f32_e32 v192, v98, v191
	v_fmac_f32_e32 v144, v126, v159
	v_fmac_f32_e32 v160, v97, v143
	v_fmac_f32_e32 v176, v129, v191
	v_fmac_f32_e32 v192, v99, v175
	v_fmac_f32_e32 v145, v96, v144
	v_fmac_f32_e32 v161, v96, v160
	v_fmac_f32_e32 v177, v98, v176
	v_fmac_f32_e32 v193, v98, v192
	v_fmac_f32_e32 v145, v126, v160
	v_fmac_f32_e32 v161, v97, v144
	v_fmac_f32_e32 v177, v129, v192
	v_fmac_f32_e32 v193, v99, v176
	v_fmac_f32_e32 v146, v96, v145
	v_fmac_f32_e32 v162, v96, v161
	v_fmac_f32_e32 v178, v98, v177
	v_fmac_f32_e32 v194, v98, v193
	v_fmac_f32_e32 v146, v126, v161
	v_fmac_f32_e32 v162, v97, v145
	v_fmac_f32_e32 v178, v129, v193
	v_fmac_f32_e32 v194, v99, v177
	v_mfma_f32_32x32x16_bf16 v[16:31], v[120:123], v[72:75], 0
	v_fmac_f32_e32 v147, v96, v146
	v_fmac_f32_e32 v163, v96, v162
	v_fmac_f32_e32 v179, v98, v178
	v_fmac_f32_e32 v195, v98, v194
	v_fmac_f32_e32 v147, v126, v162
	v_fmac_f32_e32 v163, v97, v146
	v_fmac_f32_e32 v179, v129, v194
	v_fmac_f32_e32 v195, v99, v178
	v_fmac_f32_e32 v148, v96, v147
	v_fmac_f32_e32 v164, v96, v163
	v_fmac_f32_e32 v180, v98, v179
	v_fmac_f32_e32 v196, v98, v195
	v_fmac_f32_e32 v148, v126, v163
	v_fmac_f32_e32 v164, v97, v147
	v_fmac_f32_e32 v180, v129, v195
	v_fmac_f32_e32 v196, v99, v179
	v_fmac_f32_e32 v149, v96, v148
	v_fmac_f32_e32 v165, v96, v164
	v_fmac_f32_e32 v181, v98, v180
	v_fmac_f32_e32 v197, v98, v196
	v_fmac_f32_e32 v149, v126, v164
	v_fmac_f32_e32 v165, v97, v148
	v_fmac_f32_e32 v181, v129, v196
	v_fmac_f32_e32 v197, v99, v180
	v_mfma_f32_32x32x16_bf16 v[32:47], v[120:123], v[68:71], 0
	v_fmac_f32_e32 v150, v96, v149
	v_fmac_f32_e32 v166, v96, v165
	v_fmac_f32_e32 v182, v98, v181
	v_fmac_f32_e32 v198, v98, v197
	v_fmac_f32_e32 v150, v126, v165
	v_fmac_f32_e32 v166, v97, v149
	v_fmac_f32_e32 v182, v129, v197
	v_fmac_f32_e32 v198, v99, v181
	v_fmac_f32_e32 v151, v96, v150
	v_fmac_f32_e32 v167, v96, v166
	v_fmac_f32_e32 v183, v98, v182
	v_fmac_f32_e32 v199, v98, v198
	v_fmac_f32_e32 v151, v126, v166
	v_fmac_f32_e32 v167, v97, v150
	v_fmac_f32_e32 v183, v129, v198
	v_fmac_f32_e32 v199, v99, v182
	v_fmac_f32_e32 v152, v96, v151
	v_fmac_f32_e32 v168, v96, v167
	v_fmac_f32_e32 v184, v98, v183
	v_fmac_f32_e32 v200, v98, v199
	v_fmac_f32_e32 v152, v126, v167
	v_fmac_f32_e32 v168, v97, v151
	v_fmac_f32_e32 v184, v129, v199
	v_fmac_f32_e32 v200, v99, v183
	v_mfma_f32_32x32x16_bf16 v[48:63], v[120:123], v[76:79], 0
	v_fmac_f32_e32 v153, v96, v152
	v_fmac_f32_e32 v169, v96, v168
	v_fmac_f32_e32 v185, v98, v184
	v_fmac_f32_e32 v201, v98, v200
	v_fmac_f32_e32 v153, v126, v168
	v_fmac_f32_e32 v169, v97, v152
	v_fmac_f32_e32 v185, v129, v200
	v_fmac_f32_e32 v201, v99, v184
	v_fmac_f32_e32 v154, v96, v153
	v_fmac_f32_e32 v170, v96, v169
	v_fmac_f32_e32 v186, v98, v185
	v_fmac_f32_e32 v202, v98, v201
	v_fmac_f32_e32 v154, v126, v169
	v_fmac_f32_e32 v170, v97, v153
	v_fmac_f32_e32 v186, v129, v201
	v_fmac_f32_e32 v202, v99, v185
	v_fmac_f32_e32 v155, v96, v154
	v_fmac_f32_e32 v171, v96, v170
	v_fmac_f32_e32 v187, v98, v186
	v_fmac_f32_e32 v203, v98, v202
	v_fmac_f32_e32 v155, v126, v170
	v_fmac_f32_e32 v171, v97, v154
	v_fmac_f32_e32 v187, v129, v202
	v_fmac_f32_e32 v203, v99, v186
	v_mov_b32_e32 v130, v155
	v_mov_b32_e32 v131, v171
	v_mov_b32_e32 v132, v187
	v_mov_b32_e32 v133, v203
	global_load_lds_dwordx4 v[116:117], off
	v_lshl_add_u64 v[116:117], v[116:117], 0, s[54:55]
	s_add_i32 s56, s56, -1
	s_cmp_lg_u32 s56, 0
	s_cbranch_scc1 .Ls5a_step
	s_ashr_i32 s5, s4, 31
	s_lshl_b64 s[12:13], s[4:5], 10
	v_lshl_add_u64 v[0:1], v[90:91], 0, s[12:13]
	global_store_dwordx4 v[0:1], v[130:133], off
	s_branch .LBB0_402
